# v96 + residual epilogues: packed f32 adds (residual + accumulator) as scalar add pairs in chunks 1-7
# speedup vs baseline: 1.0201x; 1.0015x over previous
.LBB0_1090:
	s_or_b64 exec, exec, s[0:1]
	v_lshl_add_u64 v[126:127], s[52:53], 0, v[32:33]
	v_add_u32_e32 v32, 0x10000, v158
	v_add_u32_e32 v122, 0x10100, v158
	s_waitcnt vmcnt(13)
	s_waitcnt lgkmcnt(0)
	v_mov_b32_e32 v153, v33
	v_lshl_add_u64 v[128:129], s[52:53], 0, v[152:153]
	v_lshlrev_b32_e32 v152, 16, v134
	v_and_b32_e32 v153, 0xffff0000, v134
	v_lshlrev_b32_e32 v134, 16, v135
	v_and_b32_e32 v135, 0xffff0000, v135
	v_lshlrev_b32_e32 v160, 16, v136
	v_and_b32_e32 v161, 0xffff0000, v136
	v_lshlrev_b32_e32 v136, 16, v137
	v_and_b32_e32 v137, 0xffff0000, v137
	v_add_f32_e32 v110, v110, v152
	v_add_f32_e32 v111, v111, v153
	v_add_f32_e32 v112, v112, v134
	v_add_f32_e32 v113, v113, v135
	v_add_f32_e32 v134, v108, v136
	v_add_f32_e32 v135, v109, v137
	v_add_f32_e32 v108, v106, v160
	v_add_f32_e32 v109, v107, v161
	v_cvt_pk_bf16_f32 v106, v110, v111
	v_mul_f32_e32 v111, v111, v111
	v_fmac_f32_e32 v111, v110, v110
	v_mul_f32_e32 v110, v113, v113
	v_fmac_f32_e32 v110, v112, v112
	v_add_f32_e32 v110, v111, v110
	v_mul_f32_e32 v111, v109, v109
	v_fmac_f32_e32 v111, v108, v108
	v_add_f32_e32 v110, v111, v110
	v_mul_f32_e32 v111, v135, v135
	v_fmac_f32_e32 v111, v134, v134
	v_cvt_pk_bf16_f32 v107, v112, v113
	v_add_f32_e32 v123, v111, v110
	v_lshlrev_b32_e32 v110, 16, v130
	v_and_b32_e32 v111, 0xffff0000, v130
	v_lshlrev_b32_e32 v112, 16, v131
	v_and_b32_e32 v113, 0xffff0000, v131
	v_lshlrev_b32_e32 v130, 16, v132
	v_and_b32_e32 v131, 0xffff0000, v132
	v_add_f32_e32 v104, v104, v112
	v_add_f32_e32 v105, v105, v113
	v_add_f32_e32 v102, v102, v110
	v_add_f32_e32 v103, v103, v111
	v_add_f32_e32 v112, v98, v130
	v_add_f32_e32 v113, v99, v131
	v_mul_f32_e32 v98, v103, v103
	v_mul_f32_e32 v99, v105, v105
	v_fmac_f32_e32 v98, v102, v102
	v_fmac_f32_e32 v99, v104, v104
	v_lshlrev_b32_e32 v132, 16, v133
	v_and_b32_e32 v133, 0xffff0000, v133
	v_add_f32_e32 v98, v98, v99
	v_mul_f32_e32 v99, v113, v113
	v_add_f32_e32 v110, v100, v132
	v_add_f32_e32 v111, v101, v133
	v_fmac_f32_e32 v99, v112, v112
	v_add_f32_e32 v98, v99, v98
	v_mul_f32_e32 v99, v111, v111
	v_fmac_f32_e32 v99, v110, v110
	v_add_f32_e32 v98, v99, v98
	v_add_f32_e32 v98, v123, v98
	v_mov_b32_e32 v99, v98
	s_nop 1
	v_permlane16_swap_b32 v99, v98
	v_cvt_pk_bf16_f32 v108, v108, v109
	v_cvt_pk_bf16_f32 v109, v134, v135
	global_store_dwordx4 v[126:127], v[106:109], off
	v_cvt_pk_bf16_f32 v100, v102, v103
	s_waitcnt lgkmcnt(0)
	v_add_f32_e32 v98, v98, v99
	v_mov_b32_e32 v99, v98
	s_nop 1
	v_permlane32_swap_b32 v99, v98
	v_cvt_pk_bf16_f32 v101, v104, v105
	v_cvt_pk_bf16_f32 v102, v112, v113
	v_cvt_pk_bf16_f32 v103, v110, v111
	global_store_dwordx4 v[128:129], v[100:103], off
	s_and_saveexec_b64 s[0:1], vcc
	s_cbranch_execz .LBB0_1092
	v_add_u32_e32 v100, 16, v150
	v_ashrrev_i32_e32 v101, 31, v100
	s_waitcnt lgkmcnt(0)
	v_add_f32_e32 v102, v98, v99
	v_lshlrev_b64 v[98:99], 6, v[100:101]
	v_lshl_add_u64 v[98:99], s[54:55], 0, v[98:99]
	v_lshl_add_u64 v[98:99], s[82:83], 2, v[98:99]
	s_lshl_b32 s16, s88, 2
	v_lshl_add_u64 v[98:99], v[98:99], 0, s[16:17]
	global_store_dword v[98:99], v102, off
.LBB0_1092:
	s_or_b64 exec, exec, s[0:1]
	v_lshl_add_u64 v[108:109], s[52:53], 0, v[32:33]
	v_add_u32_e32 v32, 0x18000, v158
	v_add_u32_e32 v106, 0x18100, v158
	v_add_u32_e32 v168, 0x58000, v158
	global_load_dwordx4 v[134:137], v168, s[52:53]
	v_add_u32_e32 v169, 0x58100, v158
	global_load_dwordx4 v[130:133], v169, s[52:53]
	s_waitcnt lgkmcnt(0)
	v_mov_b32_e32 v123, v33
	s_waitcnt vmcnt(16)
	v_lshlrev_b32_e32 v112, 16, v172
	v_and_b32_e32 v113, 0xffff0000, v172
	v_lshl_add_u64 v[110:111], s[52:53], 0, v[122:123]
	v_lshlrev_b32_e32 v118, 16, v173
	v_and_b32_e32 v119, 0xffff0000, v173
	v_lshlrev_b32_e32 v122, 16, v174
	v_and_b32_e32 v123, 0xffff0000, v174
	v_lshlrev_b32_e32 v120, 16, v175
	v_and_b32_e32 v121, 0xffff0000, v175
	v_add_f32_e32 v94, v94, v112
	v_add_f32_e32 v95, v95, v113
	v_add_f32_e32 v96, v96, v118
	v_add_f32_e32 v97, v97, v119
	v_add_f32_e32 v112, v92, v120
	v_add_f32_e32 v113, v93, v121
	v_add_f32_e32 v92, v90, v122
	v_add_f32_e32 v93, v91, v123
	v_cvt_pk_bf16_f32 v90, v94, v95
	v_mul_f32_e32 v95, v95, v95
	v_fmac_f32_e32 v95, v94, v94
	v_mul_f32_e32 v94, v97, v97
	v_fmac_f32_e32 v94, v96, v96
	v_add_f32_e32 v94, v95, v94
	v_mul_f32_e32 v95, v93, v93
	v_fmac_f32_e32 v95, v92, v92
	v_add_f32_e32 v94, v95, v94
	v_mul_f32_e32 v95, v113, v113
	v_fmac_f32_e32 v95, v112, v112
	v_cvt_pk_bf16_f32 v91, v96, v97
	v_add_f32_e32 v107, v95, v94
	v_lshlrev_b32_e32 v94, 16, v176
	v_and_b32_e32 v95, 0xffff0000, v176
	v_lshlrev_b32_e32 v96, 16, v177
	v_and_b32_e32 v97, 0xffff0000, v177
	v_lshlrev_b32_e32 v114, 16, v178
	v_and_b32_e32 v115, 0xffff0000, v178
	v_add_f32_e32 v88, v88, v96
	v_add_f32_e32 v89, v89, v97
	v_add_f32_e32 v86, v86, v94
	v_add_f32_e32 v87, v87, v95
	v_add_f32_e32 v96, v82, v114
	v_add_f32_e32 v97, v83, v115
	v_mul_f32_e32 v82, v87, v87
	v_mul_f32_e32 v83, v89, v89
	v_fmac_f32_e32 v82, v86, v86
	v_fmac_f32_e32 v83, v88, v88
	v_lshlrev_b32_e32 v116, 16, v179
	v_and_b32_e32 v117, 0xffff0000, v179
	v_add_f32_e32 v82, v82, v83
	v_mul_f32_e32 v83, v97, v97
	v_add_f32_e32 v94, v84, v116
	v_add_f32_e32 v95, v85, v117
	v_fmac_f32_e32 v83, v96, v96
	v_add_f32_e32 v82, v83, v82
	v_mul_f32_e32 v83, v95, v95
	v_fmac_f32_e32 v83, v94, v94
	v_add_f32_e32 v82, v83, v82
	v_add_f32_e32 v82, v107, v82
	v_mov_b32_e32 v83, v82
	s_nop 1
	v_permlane16_swap_b32 v83, v82
	v_cvt_pk_bf16_f32 v92, v92, v93
	v_cvt_pk_bf16_f32 v93, v112, v113
	global_store_dwordx4 v[108:109], v[90:93], off
	v_cvt_pk_bf16_f32 v84, v86, v87
	s_waitcnt lgkmcnt(0)
	v_add_f32_e32 v82, v82, v83
	v_mov_b32_e32 v83, v82
	s_nop 1
	v_permlane32_swap_b32 v83, v82
	v_cvt_pk_bf16_f32 v85, v88, v89
	v_cvt_pk_bf16_f32 v86, v96, v97
	v_cvt_pk_bf16_f32 v87, v94, v95
	global_store_dwordx4 v[110:111], v[84:87], off
	s_and_saveexec_b64 s[0:1], vcc
	s_cbranch_execz .LBB0_1094
	v_add_u32_e32 v84, 32, v150
	v_ashrrev_i32_e32 v85, 31, v84
	s_waitcnt lgkmcnt(0)
	v_add_f32_e32 v86, v82, v83
	v_lshlrev_b64 v[82:83], 6, v[84:85]
	v_lshl_add_u64 v[82:83], s[54:55], 0, v[82:83]
	v_lshl_add_u64 v[82:83], s[82:83], 2, v[82:83]
	s_lshl_b32 s16, s88, 2
	v_lshl_add_u64 v[82:83], v[82:83], 0, s[16:17]
	global_store_dword v[82:83], v86, off
.LBB0_1094:
	s_or_b64 exec, exec, s[0:1]
	v_lshl_add_u64 v[92:93], s[52:53], 0, v[32:33]
	v_add_u32_e32 v32, 0x40000, v158
	v_add_u32_e32 v90, 0x40100, v158
	s_waitcnt lgkmcnt(0)
	v_mov_b32_e32 v107, v33
	s_waitcnt vmcnt(17)
	v_lshlrev_b32_e32 v96, 16, v180
	v_and_b32_e32 v97, 0xffff0000, v180
	v_lshl_add_u64 v[94:95], s[52:53], 0, v[106:107]
	v_lshlrev_b32_e32 v102, 16, v181
	v_and_b32_e32 v103, 0xffff0000, v181
	v_lshlrev_b32_e32 v106, 16, v182
	v_and_b32_e32 v107, 0xffff0000, v182
	v_lshlrev_b32_e32 v104, 16, v183
	v_and_b32_e32 v105, 0xffff0000, v183
	v_add_f32_e32 v78, v78, v96
	v_add_f32_e32 v79, v79, v97
	v_add_f32_e32 v80, v80, v102
	v_add_f32_e32 v81, v81, v103
	v_add_f32_e32 v96, v76, v104
	v_add_f32_e32 v97, v77, v105
	v_add_f32_e32 v76, v74, v106
	v_add_f32_e32 v77, v75, v107
	v_cvt_pk_bf16_f32 v74, v78, v79
	v_mul_f32_e32 v79, v79, v79
	v_fmac_f32_e32 v79, v78, v78
	v_mul_f32_e32 v78, v81, v81
	v_fmac_f32_e32 v78, v80, v80
	v_add_f32_e32 v78, v79, v78
	v_mul_f32_e32 v79, v77, v77
	v_fmac_f32_e32 v79, v76, v76
	v_add_f32_e32 v78, v79, v78
	v_mul_f32_e32 v79, v97, v97
	v_fmac_f32_e32 v79, v96, v96
	v_cvt_pk_bf16_f32 v75, v80, v81
	v_add_f32_e32 v91, v79, v78
	v_lshlrev_b32_e32 v78, 16, v186
	v_and_b32_e32 v79, 0xffff0000, v186
	v_lshlrev_b32_e32 v80, 16, v187
	v_and_b32_e32 v81, 0xffff0000, v187
	v_lshlrev_b32_e32 v98, 16, v188
	v_and_b32_e32 v99, 0xffff0000, v188
	v_add_f32_e32 v72, v72, v80
	v_add_f32_e32 v73, v73, v81
	v_add_f32_e32 v70, v70, v78
	v_add_f32_e32 v71, v71, v79
	v_add_f32_e32 v80, v66, v98
	v_add_f32_e32 v81, v67, v99
	v_mul_f32_e32 v66, v71, v71
	v_mul_f32_e32 v67, v73, v73
	v_fmac_f32_e32 v66, v70, v70
	v_fmac_f32_e32 v67, v72, v72
	v_lshlrev_b32_e32 v100, 16, v189
	v_and_b32_e32 v101, 0xffff0000, v189
	v_add_f32_e32 v66, v66, v67
	v_mul_f32_e32 v67, v81, v81
	v_add_f32_e32 v78, v68, v100
	v_add_f32_e32 v79, v69, v101
	v_fmac_f32_e32 v67, v80, v80
	v_add_f32_e32 v66, v67, v66
	v_mul_f32_e32 v67, v79, v79
	v_fmac_f32_e32 v67, v78, v78
	v_add_f32_e32 v66, v67, v66
	v_add_f32_e32 v66, v91, v66
	v_mov_b32_e32 v67, v66
	s_nop 1
	v_permlane16_swap_b32 v67, v66
	v_cvt_pk_bf16_f32 v76, v76, v77
	v_cvt_pk_bf16_f32 v77, v96, v97
	global_store_dwordx4 v[92:93], v[74:77], off
	v_cvt_pk_bf16_f32 v68, v70, v71
	s_waitcnt lgkmcnt(0)
	v_add_f32_e32 v66, v66, v67
	v_mov_b32_e32 v67, v66
	s_nop 1
	v_permlane32_swap_b32 v67, v66
	v_cvt_pk_bf16_f32 v69, v72, v73
	v_cvt_pk_bf16_f32 v70, v80, v81
	v_cvt_pk_bf16_f32 v71, v78, v79
	global_store_dwordx4 v[94:95], v[68:71], off
	s_and_saveexec_b64 s[0:1], vcc
	s_cbranch_execz .LBB0_1096
	v_add_u32_e32 v68, 48, v150
	v_ashrrev_i32_e32 v69, 31, v68
	s_waitcnt lgkmcnt(0)
	v_add_f32_e32 v70, v66, v67
	v_lshlrev_b64 v[66:67], 6, v[68:69]
	v_lshl_add_u64 v[66:67], s[54:55], 0, v[66:67]
	v_lshl_add_u64 v[66:67], s[82:83], 2, v[66:67]
	s_lshl_b32 s16, s88, 2
	v_lshl_add_u64 v[66:67], v[66:67], 0, s[16:17]
	global_store_dword v[66:67], v70, off
.LBB0_1096:
	s_or_b64 exec, exec, s[0:1]
	v_lshl_add_u64 v[76:77], s[52:53], 0, v[32:33]
	v_add_u32_e32 v32, 0x48000, v158
	v_add_u32_e32 v74, 0x48100, v158
	s_waitcnt lgkmcnt(0)
	v_mov_b32_e32 v91, v33
	s_waitcnt vmcnt(18)
	v_lshlrev_b32_e32 v80, 16, v190
	v_and_b32_e32 v81, 0xffff0000, v190
	v_lshl_add_u64 v[78:79], s[52:53], 0, v[90:91]
	v_lshlrev_b32_e32 v86, 16, v191
	v_and_b32_e32 v87, 0xffff0000, v191
	v_lshlrev_b32_e32 v90, 16, v192
	v_and_b32_e32 v91, 0xffff0000, v192
	v_lshlrev_b32_e32 v88, 16, v193
	v_and_b32_e32 v89, 0xffff0000, v193
	v_add_f32_e32 v62, v62, v80
	v_add_f32_e32 v63, v63, v81
	v_add_f32_e32 v64, v64, v86
	v_add_f32_e32 v65, v65, v87
	v_add_f32_e32 v80, v60, v88
	v_add_f32_e32 v81, v61, v89
	v_add_f32_e32 v60, v58, v90
	v_add_f32_e32 v61, v59, v91
	v_cvt_pk_bf16_f32 v58, v62, v63
	v_mul_f32_e32 v63, v63, v63
	v_fmac_f32_e32 v63, v62, v62
	v_mul_f32_e32 v62, v65, v65
	v_fmac_f32_e32 v62, v64, v64
	v_add_f32_e32 v62, v63, v62
	v_mul_f32_e32 v63, v61, v61
	v_fmac_f32_e32 v63, v60, v60
	v_add_f32_e32 v62, v63, v62
	v_mul_f32_e32 v63, v81, v81
	v_fmac_f32_e32 v63, v80, v80
	v_cvt_pk_bf16_f32 v59, v64, v65
	v_add_f32_e32 v75, v63, v62
	v_lshlrev_b32_e32 v62, 16, v202
	v_and_b32_e32 v63, 0xffff0000, v202
	v_lshlrev_b32_e32 v64, 16, v203
	v_and_b32_e32 v65, 0xffff0000, v203
	v_lshlrev_b32_e32 v82, 16, v204
	v_and_b32_e32 v83, 0xffff0000, v204
	v_add_f32_e32 v56, v56, v64
	v_add_f32_e32 v57, v57, v65
	v_add_f32_e32 v54, v54, v62
	v_add_f32_e32 v55, v55, v63
	v_add_f32_e32 v64, v50, v82
	v_add_f32_e32 v65, v51, v83
	v_mul_f32_e32 v50, v55, v55
	v_mul_f32_e32 v51, v57, v57
	v_fmac_f32_e32 v50, v54, v54
	v_fmac_f32_e32 v51, v56, v56
	v_lshlrev_b32_e32 v84, 16, v205
	v_and_b32_e32 v85, 0xffff0000, v205
	v_add_f32_e32 v50, v50, v51
	v_mul_f32_e32 v51, v65, v65
	v_add_f32_e32 v62, v52, v84
	v_add_f32_e32 v63, v53, v85
	v_fmac_f32_e32 v51, v64, v64
	v_add_f32_e32 v50, v51, v50
	v_mul_f32_e32 v51, v63, v63
	v_fmac_f32_e32 v51, v62, v62
	v_add_f32_e32 v50, v51, v50
	v_add_f32_e32 v50, v75, v50
	v_mov_b32_e32 v51, v50
	s_nop 1
	v_permlane16_swap_b32 v51, v50
	v_cvt_pk_bf16_f32 v60, v60, v61
	v_cvt_pk_bf16_f32 v61, v80, v81
	global_store_dwordx4 v[76:77], v[58:61], off
	v_cvt_pk_bf16_f32 v52, v54, v55
	s_waitcnt lgkmcnt(0)
	v_add_f32_e32 v50, v50, v51
	v_mov_b32_e32 v51, v50
	s_nop 1
	v_permlane32_swap_b32 v51, v50
	v_cvt_pk_bf16_f32 v53, v56, v57
	v_cvt_pk_bf16_f32 v54, v64, v65
	v_cvt_pk_bf16_f32 v55, v62, v63
	global_store_dwordx4 v[78:79], v[52:55], off
	s_and_saveexec_b64 s[0:1], vcc
	s_cbranch_execz .LBB0_1098
	v_add_u32_e32 v52, 0x80, v150
	v_ashrrev_i32_e32 v53, 31, v52
	s_waitcnt lgkmcnt(0)
	v_add_f32_e32 v54, v50, v51
	v_lshlrev_b64 v[50:51], 6, v[52:53]
	v_lshl_add_u64 v[50:51], s[54:55], 0, v[50:51]
	v_lshl_add_u64 v[50:51], s[82:83], 2, v[50:51]
	s_lshl_b32 s16, s88, 2
	v_lshl_add_u64 v[50:51], v[50:51], 0, s[16:17]
	global_store_dword v[50:51], v54, off
.LBB0_1098:
	s_or_b64 exec, exec, s[0:1]
	v_lshl_add_u64 v[60:61], s[52:53], 0, v[32:33]
	v_add_u32_e32 v32, 0x50000, v158
	v_add_u32_e32 v58, 0x50100, v158
	s_waitcnt lgkmcnt(0)
	v_mov_b32_e32 v75, v33
	s_waitcnt vmcnt(19)
	v_lshlrev_b32_e32 v64, 16, v206
	v_and_b32_e32 v65, 0xffff0000, v206
	v_lshl_add_u64 v[62:63], s[52:53], 0, v[74:75]
	v_lshlrev_b32_e32 v70, 16, v207
	v_and_b32_e32 v71, 0xffff0000, v207
	v_lshlrev_b32_e32 v74, 16, v208
	v_and_b32_e32 v75, 0xffff0000, v208
	v_lshlrev_b32_e32 v72, 16, v209
	v_and_b32_e32 v73, 0xffff0000, v209
	v_add_f32_e32 v46, v46, v64
	v_add_f32_e32 v47, v47, v65
	v_add_f32_e32 v48, v48, v70
	v_add_f32_e32 v49, v49, v71
	v_add_f32_e32 v64, v44, v72
	v_add_f32_e32 v65, v45, v73
	v_add_f32_e32 v44, v42, v74
	v_add_f32_e32 v45, v43, v75
	v_cvt_pk_bf16_f32 v42, v46, v47
	v_mul_f32_e32 v47, v47, v47
	v_fmac_f32_e32 v47, v46, v46
	v_mul_f32_e32 v46, v49, v49
	v_fmac_f32_e32 v46, v48, v48
	v_add_f32_e32 v46, v47, v46
	v_mul_f32_e32 v47, v45, v45
	v_fmac_f32_e32 v47, v44, v44
	v_add_f32_e32 v46, v47, v46
	v_mul_f32_e32 v47, v65, v65
	v_fmac_f32_e32 v47, v64, v64
	v_cvt_pk_bf16_f32 v43, v48, v49
	v_add_f32_e32 v59, v47, v46
	v_lshlrev_b32_e32 v46, 16, v210
	v_and_b32_e32 v47, 0xffff0000, v210
	v_lshlrev_b32_e32 v48, 16, v211
	v_and_b32_e32 v49, 0xffff0000, v211
	v_lshlrev_b32_e32 v66, 16, v212
	v_and_b32_e32 v67, 0xffff0000, v212
	v_add_f32_e32 v40, v40, v48
	v_add_f32_e32 v41, v41, v49
	v_add_f32_e32 v38, v38, v46
	v_add_f32_e32 v39, v39, v47
	v_add_f32_e32 v48, v34, v66
	v_add_f32_e32 v49, v35, v67
	v_mul_f32_e32 v34, v39, v39
	v_mul_f32_e32 v35, v41, v41
	v_fmac_f32_e32 v34, v38, v38
	v_fmac_f32_e32 v35, v40, v40
	v_lshlrev_b32_e32 v68, 16, v213
	v_and_b32_e32 v69, 0xffff0000, v213
	v_add_f32_e32 v34, v34, v35
	v_mul_f32_e32 v35, v49, v49
	v_add_f32_e32 v46, v36, v68
	v_add_f32_e32 v47, v37, v69
	v_fmac_f32_e32 v35, v48, v48
	v_add_f32_e32 v34, v35, v34
	v_mul_f32_e32 v35, v47, v47
	v_fmac_f32_e32 v35, v46, v46
	v_add_f32_e32 v34, v35, v34
	v_add_f32_e32 v34, v59, v34
	v_mov_b32_e32 v35, v34
	s_nop 1
	v_permlane16_swap_b32 v35, v34
	v_cvt_pk_bf16_f32 v44, v44, v45
	v_cvt_pk_bf16_f32 v45, v64, v65
	global_store_dwordx4 v[60:61], v[42:45], off
	v_cvt_pk_bf16_f32 v36, v38, v39
	s_waitcnt lgkmcnt(0)
	v_add_f32_e32 v34, v34, v35
	v_mov_b32_e32 v35, v34
	s_nop 1
	v_permlane32_swap_b32 v35, v34
	v_cvt_pk_bf16_f32 v37, v40, v41
	v_cvt_pk_bf16_f32 v38, v48, v49
	v_cvt_pk_bf16_f32 v39, v46, v47
	global_store_dwordx4 v[62:63], v[36:39], off
	s_and_saveexec_b64 s[0:1], vcc
	s_cbranch_execz .LBB0_1100
	v_add_u32_e32 v36, 0x90, v150
	v_ashrrev_i32_e32 v37, 31, v36
	s_waitcnt lgkmcnt(0)
	v_add_f32_e32 v38, v34, v35
	v_lshlrev_b64 v[34:35], 6, v[36:37]
	v_lshl_add_u64 v[34:35], s[54:55], 0, v[34:35]
	v_lshl_add_u64 v[34:35], s[82:83], 2, v[34:35]
	s_lshl_b32 s16, s88, 2
	v_lshl_add_u64 v[34:35], v[34:35], 0, s[16:17]
	global_store_dword v[34:35], v38, off
.LBB0_1100:
	s_or_b64 exec, exec, s[0:1]
	v_lshl_add_u64 v[44:45], s[52:53], 0, v[32:33]
	v_add_u32_e32 v32, 0x58000, v158
	v_add_u32_e32 v42, 0x58100, v158
	s_waitcnt lgkmcnt(0)
	v_mov_b32_e32 v59, v33
	s_waitcnt vmcnt(20)
	v_lshlrev_b32_e32 v48, 16, v214
	v_and_b32_e32 v49, 0xffff0000, v214
	v_lshl_add_u64 v[46:47], s[52:53], 0, v[58:59]
	v_lshlrev_b32_e32 v54, 16, v215
	v_and_b32_e32 v55, 0xffff0000, v215
	v_lshlrev_b32_e32 v58, 16, v216
	v_and_b32_e32 v59, 0xffff0000, v216
	v_lshlrev_b32_e32 v56, 16, v217
	v_and_b32_e32 v57, 0xffff0000, v217
	v_add_f32_e32 v28, v28, v48
	v_add_f32_e32 v29, v29, v49
	v_add_f32_e32 v30, v30, v54
	v_add_f32_e32 v31, v31, v55
	v_add_f32_e32 v48, v26, v56
	v_add_f32_e32 v49, v27, v57
	v_add_f32_e32 v26, v24, v58
	v_add_f32_e32 v27, v25, v59
	v_cvt_pk_bf16_f32 v24, v28, v29
	v_mul_f32_e32 v29, v29, v29
	v_fmac_f32_e32 v29, v28, v28
	v_mul_f32_e32 v28, v31, v31
	v_fmac_f32_e32 v28, v30, v30
	v_add_f32_e32 v28, v29, v28
	v_mul_f32_e32 v29, v27, v27
	v_fmac_f32_e32 v29, v26, v26
	v_add_f32_e32 v28, v29, v28
	v_mul_f32_e32 v29, v49, v49
	v_fmac_f32_e32 v29, v48, v48
	v_cvt_pk_bf16_f32 v25, v30, v31
	v_add_f32_e32 v43, v29, v28
	v_lshlrev_b32_e32 v28, 16, v218
	v_and_b32_e32 v29, 0xffff0000, v218
	v_lshlrev_b32_e32 v30, 16, v219
	v_and_b32_e32 v31, 0xffff0000, v219
	v_lshlrev_b32_e32 v50, 16, v220
	v_and_b32_e32 v51, 0xffff0000, v220
	v_add_f32_e32 v22, v22, v30
	v_add_f32_e32 v23, v23, v31
	v_add_f32_e32 v20, v20, v28
	v_add_f32_e32 v21, v21, v29
	v_add_f32_e32 v30, v16, v50
	v_add_f32_e32 v31, v17, v51
	v_mul_f32_e32 v16, v21, v21
	v_mul_f32_e32 v17, v23, v23
	v_fmac_f32_e32 v16, v20, v20
	v_fmac_f32_e32 v17, v22, v22
	v_lshlrev_b32_e32 v52, 16, v221
	v_and_b32_e32 v53, 0xffff0000, v221
	v_add_f32_e32 v16, v16, v17
	v_mul_f32_e32 v17, v31, v31
	v_add_f32_e32 v28, v18, v52
	v_add_f32_e32 v29, v19, v53
	v_fmac_f32_e32 v17, v30, v30
	v_add_f32_e32 v16, v17, v16
	v_mul_f32_e32 v17, v29, v29
	v_fmac_f32_e32 v17, v28, v28
	v_add_f32_e32 v16, v17, v16
	v_add_f32_e32 v16, v43, v16
	v_mov_b32_e32 v17, v16
	s_nop 1
	v_permlane16_swap_b32 v17, v16
	v_cvt_pk_bf16_f32 v26, v26, v27
	v_cvt_pk_bf16_f32 v27, v48, v49
	global_store_dwordx4 v[44:45], v[24:27], off
	v_cvt_pk_bf16_f32 v18, v20, v21
	s_waitcnt lgkmcnt(0)
	v_add_f32_e32 v16, v16, v17
	v_mov_b32_e32 v17, v16
	s_nop 1
	v_permlane32_swap_b32 v17, v16
	v_cvt_pk_bf16_f32 v19, v22, v23
	v_cvt_pk_bf16_f32 v20, v30, v31
	v_cvt_pk_bf16_f32 v21, v28, v29
	global_store_dwordx4 v[46:47], v[18:21], off
	s_and_saveexec_b64 s[0:1], vcc
	s_cbranch_execz .LBB0_1102
	v_add_u32_e32 v18, 0xa0, v150
	v_ashrrev_i32_e32 v19, 31, v18
	s_waitcnt lgkmcnt(0)
	v_add_f32_e32 v20, v16, v17
	v_lshlrev_b64 v[16:17], 6, v[18:19]
	v_lshl_add_u64 v[16:17], s[54:55], 0, v[16:17]
	v_lshl_add_u64 v[16:17], s[82:83], 2, v[16:17]
	s_lshl_b32 s16, s88, 2
	v_lshl_add_u64 v[16:17], v[16:17], 0, s[16:17]
	global_store_dword v[16:17], v20, off
.LBB0_1102:
	s_or_b64 exec, exec, s[0:1]
	s_waitcnt vmcnt(15)
	v_lshlrev_b32_e32 v20, 16, v134
	v_and_b32_e32 v21, 0xffff0000, v134
	v_lshlrev_b32_e32 v22, 16, v135
	v_and_b32_e32 v23, 0xffff0000, v135
	v_lshlrev_b32_e32 v24, 16, v136
	v_and_b32_e32 v25, 0xffff0000, v136
	v_lshlrev_b32_e32 v26, 16, v137
	v_and_b32_e32 v27, 0xffff0000, v137
	v_add_f32_e32 v12, v12, v20
	v_add_f32_e32 v13, v13, v21
	v_add_f32_e32 v14, v14, v22
	v_add_f32_e32 v15, v15, v23
	v_add_f32_e32 v20, v10, v26
	v_add_f32_e32 v21, v11, v27
	v_add_f32_e32 v10, v8, v24
	v_add_f32_e32 v11, v9, v25
	v_cvt_pk_bf16_f32 v8, v12, v13
	v_mul_f32_e32 v13, v13, v13
	v_fmac_f32_e32 v13, v12, v12
	v_mul_f32_e32 v12, v15, v15
	v_fmac_f32_e32 v12, v14, v14
	v_add_f32_e32 v12, v13, v12
	v_mul_f32_e32 v13, v11, v11
	v_fmac_f32_e32 v13, v10, v10
	v_add_f32_e32 v12, v13, v12
	v_mul_f32_e32 v13, v21, v21
	v_fmac_f32_e32 v13, v20, v20
	v_cvt_pk_bf16_f32 v9, v14, v15
	v_add_f32_e32 v26, v13, v12
	v_lshlrev_b32_e32 v12, 16, v130
	v_and_b32_e32 v13, 0xffff0000, v130
	v_lshlrev_b32_e32 v14, 16, v131
	v_and_b32_e32 v15, 0xffff0000, v131
	v_lshlrev_b32_e32 v22, 16, v132
	v_and_b32_e32 v23, 0xffff0000, v132
	v_add_f32_e32 v6, v6, v14
	v_add_f32_e32 v7, v7, v15
	v_add_f32_e32 v4, v4, v12
	v_add_f32_e32 v5, v5, v13
	v_add_f32_e32 v14, v0, v22
	v_add_f32_e32 v15, v1, v23
	v_mul_f32_e32 v0, v5, v5
	v_mul_f32_e32 v1, v7, v7
	v_fmac_f32_e32 v0, v4, v4
	v_fmac_f32_e32 v1, v6, v6
	v_lshlrev_b32_e32 v24, 16, v133
	v_and_b32_e32 v25, 0xffff0000, v133
	v_add_f32_e32 v0, v0, v1
	v_mul_f32_e32 v1, v15, v15
	v_add_f32_e32 v12, v2, v24
	v_add_f32_e32 v13, v3, v25
	v_fmac_f32_e32 v1, v14, v14
	v_add_f32_e32 v0, v1, v0
	v_mul_f32_e32 v1, v13, v13
	v_fmac_f32_e32 v1, v12, v12
	v_add_f32_e32 v0, v1, v0
	v_add_f32_e32 v0, v26, v0
	v_mov_b32_e32 v1, v0
	s_nop 1
	v_permlane16_swap_b32 v1, v0
	v_mov_b32_e32 v43, v33
	s_waitcnt lgkmcnt(1)
	v_lshl_add_u64 v[16:17], s[52:53], 0, v[32:33]
	v_lshl_add_u64 v[18:19], s[52:53], 0, v[42:43]
	v_cvt_pk_bf16_f32 v10, v10, v11
	s_waitcnt lgkmcnt(0)
	v_add_f32_e32 v0, v0, v1
	v_mov_b32_e32 v1, v0
	s_nop 1
	v_permlane32_swap_b32 v1, v0
	v_cvt_pk_bf16_f32 v11, v20, v21
	global_store_dwordx4 v[16:17], v[8:11], off
	v_cvt_pk_bf16_f32 v2, v4, v5
	v_cvt_pk_bf16_f32 v3, v6, v7
	v_cvt_pk_bf16_f32 v4, v14, v15
	v_cvt_pk_bf16_f32 v5, v12, v13
	global_store_dwordx4 v[18:19], v[2:5], off
	s_and_saveexec_b64 s[0:1], vcc
	s_cbranch_execz .LBB0_1104
	v_add_u32_e32 v2, 0xb0, v150
	v_ashrrev_i32_e32 v3, 31, v2
	s_waitcnt lgkmcnt(0)
	v_add_f32_e32 v4, v0, v1
	v_lshlrev_b64 v[0:1], 6, v[2:3]
	v_lshl_add_u64 v[0:1], s[54:55], 0, v[0:1]
	v_lshl_add_u64 v[0:1], s[82:83], 2, v[0:1]
	s_lshl_b32 s16, s88, 2
	v_lshl_add_u64 v[0:1], v[0:1], 0, s[16:17]
	global_store_dword v[0:1], v4, off

.LBB0_1274:
	s_or_b64 exec, exec, s[0:1]
	v_lshl_add_u64 v[126:127], s[42:43], 0, v[32:33]
	v_add_u32_e32 v32, 0x10000, v158
	v_add_u32_e32 v122, 0x10100, v158
	s_waitcnt vmcnt(13)
	s_waitcnt lgkmcnt(0)
	v_mov_b32_e32 v153, v33
	v_lshl_add_u64 v[128:129], s[42:43], 0, v[152:153]
	v_lshlrev_b32_e32 v152, 16, v134
	v_and_b32_e32 v153, 0xffff0000, v134
	v_lshlrev_b32_e32 v134, 16, v135
	v_and_b32_e32 v135, 0xffff0000, v135
	v_lshlrev_b32_e32 v160, 16, v136
	v_and_b32_e32 v161, 0xffff0000, v136
	v_lshlrev_b32_e32 v136, 16, v137
	v_and_b32_e32 v137, 0xffff0000, v137
	v_add_f32_e32 v110, v110, v152
	v_add_f32_e32 v111, v111, v153
	v_add_f32_e32 v112, v112, v134
	v_add_f32_e32 v113, v113, v135
	v_add_f32_e32 v134, v108, v136
	v_add_f32_e32 v135, v109, v137
	v_add_f32_e32 v108, v106, v160
	v_add_f32_e32 v109, v107, v161
	v_cvt_pk_bf16_f32 v106, v110, v111
	v_mul_f32_e32 v111, v111, v111
	v_fmac_f32_e32 v111, v110, v110
	v_mul_f32_e32 v110, v113, v113
	v_fmac_f32_e32 v110, v112, v112
	v_add_f32_e32 v110, v111, v110
	v_mul_f32_e32 v111, v109, v109
	v_fmac_f32_e32 v111, v108, v108
	v_add_f32_e32 v110, v111, v110
	v_mul_f32_e32 v111, v135, v135
	v_fmac_f32_e32 v111, v134, v134
	v_cvt_pk_bf16_f32 v107, v112, v113
	v_add_f32_e32 v123, v111, v110
	v_lshlrev_b32_e32 v110, 16, v130
	v_and_b32_e32 v111, 0xffff0000, v130
	v_lshlrev_b32_e32 v112, 16, v131
	v_and_b32_e32 v113, 0xffff0000, v131
	v_lshlrev_b32_e32 v130, 16, v132
	v_and_b32_e32 v131, 0xffff0000, v132
	v_add_f32_e32 v104, v104, v112
	v_add_f32_e32 v105, v105, v113
	v_add_f32_e32 v102, v102, v110
	v_add_f32_e32 v103, v103, v111
	v_add_f32_e32 v112, v98, v130
	v_add_f32_e32 v113, v99, v131
	v_mul_f32_e32 v98, v103, v103
	v_mul_f32_e32 v99, v105, v105
	v_fmac_f32_e32 v98, v102, v102
	v_fmac_f32_e32 v99, v104, v104
	v_lshlrev_b32_e32 v132, 16, v133
	v_and_b32_e32 v133, 0xffff0000, v133
	v_add_f32_e32 v98, v98, v99
	v_mul_f32_e32 v99, v113, v113
	v_add_f32_e32 v110, v100, v132
	v_add_f32_e32 v111, v101, v133
	v_fmac_f32_e32 v99, v112, v112
	v_add_f32_e32 v98, v99, v98
	v_mul_f32_e32 v99, v111, v111
	v_fmac_f32_e32 v99, v110, v110
	v_add_f32_e32 v98, v99, v98
	v_add_f32_e32 v98, v123, v98
	v_mov_b32_e32 v99, v98
	s_nop 1
	v_permlane16_swap_b32 v99, v98
	v_cvt_pk_bf16_f32 v108, v108, v109
	v_cvt_pk_bf16_f32 v109, v134, v135
	global_store_dwordx4 v[126:127], v[106:109], off
	v_cvt_pk_bf16_f32 v100, v102, v103
	s_waitcnt lgkmcnt(0)
	v_add_f32_e32 v98, v98, v99
	v_mov_b32_e32 v99, v98
	s_nop 1
	v_permlane32_swap_b32 v99, v98
	v_cvt_pk_bf16_f32 v101, v104, v105
	v_cvt_pk_bf16_f32 v102, v112, v113
	v_cvt_pk_bf16_f32 v103, v110, v111
	global_store_dwordx4 v[128:129], v[100:103], off
	s_and_saveexec_b64 s[0:1], vcc
	s_cbranch_execz .LBB0_1276
	v_add_u32_e32 v100, 16, v150
	v_ashrrev_i32_e32 v101, 31, v100
	s_waitcnt lgkmcnt(0)
	v_add_f32_e32 v102, v98, v99
	v_lshlrev_b64 v[98:99], 6, v[100:101]
	v_lshl_add_u64 v[98:99], s[44:45], 0, v[98:99]
	v_lshl_add_u64 v[98:99], s[70:71], 2, v[98:99]
	s_lshl_b32 s16, s86, 2
	v_lshl_add_u64 v[98:99], v[98:99], 0, s[16:17]
	global_store_dword v[98:99], v102, off
.LBB0_1276:
	s_or_b64 exec, exec, s[0:1]
	v_lshl_add_u64 v[108:109], s[42:43], 0, v[32:33]
	v_add_u32_e32 v32, 0x18000, v158
	v_add_u32_e32 v106, 0x18100, v158
	v_add_u32_e32 v168, 0x58000, v158
	global_load_dwordx4 v[134:137], v168, s[42:43]
	v_add_u32_e32 v169, 0x58100, v158
	global_load_dwordx4 v[130:133], v169, s[42:43]
	s_waitcnt lgkmcnt(0)
	v_mov_b32_e32 v123, v33
	s_waitcnt vmcnt(16)
	v_lshlrev_b32_e32 v112, 16, v172
	v_and_b32_e32 v113, 0xffff0000, v172
	v_lshl_add_u64 v[110:111], s[42:43], 0, v[122:123]
	v_lshlrev_b32_e32 v118, 16, v173
	v_and_b32_e32 v119, 0xffff0000, v173
	v_lshlrev_b32_e32 v122, 16, v174
	v_and_b32_e32 v123, 0xffff0000, v174
	v_lshlrev_b32_e32 v120, 16, v175
	v_and_b32_e32 v121, 0xffff0000, v175
	v_add_f32_e32 v94, v94, v112
	v_add_f32_e32 v95, v95, v113
	v_add_f32_e32 v96, v96, v118
	v_add_f32_e32 v97, v97, v119
	v_add_f32_e32 v112, v92, v120
	v_add_f32_e32 v113, v93, v121
	v_add_f32_e32 v92, v90, v122
	v_add_f32_e32 v93, v91, v123
	v_cvt_pk_bf16_f32 v90, v94, v95
	v_mul_f32_e32 v95, v95, v95
	v_fmac_f32_e32 v95, v94, v94
	v_mul_f32_e32 v94, v97, v97
	v_fmac_f32_e32 v94, v96, v96
	v_add_f32_e32 v94, v95, v94
	v_mul_f32_e32 v95, v93, v93
	v_fmac_f32_e32 v95, v92, v92
	v_add_f32_e32 v94, v95, v94
	v_mul_f32_e32 v95, v113, v113
	v_fmac_f32_e32 v95, v112, v112
	v_cvt_pk_bf16_f32 v91, v96, v97
	v_add_f32_e32 v107, v95, v94
	v_lshlrev_b32_e32 v94, 16, v176
	v_and_b32_e32 v95, 0xffff0000, v176
	v_lshlrev_b32_e32 v96, 16, v177
	v_and_b32_e32 v97, 0xffff0000, v177
	v_lshlrev_b32_e32 v114, 16, v178
	v_and_b32_e32 v115, 0xffff0000, v178
	v_add_f32_e32 v88, v88, v96
	v_add_f32_e32 v89, v89, v97
	v_add_f32_e32 v86, v86, v94
	v_add_f32_e32 v87, v87, v95
	v_add_f32_e32 v96, v82, v114
	v_add_f32_e32 v97, v83, v115
	v_mul_f32_e32 v82, v87, v87
	v_mul_f32_e32 v83, v89, v89
	v_fmac_f32_e32 v82, v86, v86
	v_fmac_f32_e32 v83, v88, v88
	v_lshlrev_b32_e32 v116, 16, v179
	v_and_b32_e32 v117, 0xffff0000, v179
	v_add_f32_e32 v82, v82, v83
	v_mul_f32_e32 v83, v97, v97
	v_add_f32_e32 v94, v84, v116
	v_add_f32_e32 v95, v85, v117
	v_fmac_f32_e32 v83, v96, v96
	v_add_f32_e32 v82, v83, v82
	v_mul_f32_e32 v83, v95, v95
	v_fmac_f32_e32 v83, v94, v94
	v_add_f32_e32 v82, v83, v82
	v_add_f32_e32 v82, v107, v82
	v_mov_b32_e32 v83, v82
	s_nop 1
	v_permlane16_swap_b32 v83, v82
	v_cvt_pk_bf16_f32 v92, v92, v93
	v_cvt_pk_bf16_f32 v93, v112, v113
	global_store_dwordx4 v[108:109], v[90:93], off
	v_cvt_pk_bf16_f32 v84, v86, v87
	s_waitcnt lgkmcnt(0)
	v_add_f32_e32 v82, v82, v83
	v_mov_b32_e32 v83, v82
	s_nop 1
	v_permlane32_swap_b32 v83, v82
	v_cvt_pk_bf16_f32 v85, v88, v89
	v_cvt_pk_bf16_f32 v86, v96, v97
	v_cvt_pk_bf16_f32 v87, v94, v95
	global_store_dwordx4 v[110:111], v[84:87], off
	s_and_saveexec_b64 s[0:1], vcc
	s_cbranch_execz .LBB0_1278
	v_add_u32_e32 v84, 32, v150
	v_ashrrev_i32_e32 v85, 31, v84
	s_waitcnt lgkmcnt(0)
	v_add_f32_e32 v86, v82, v83
	v_lshlrev_b64 v[82:83], 6, v[84:85]
	v_lshl_add_u64 v[82:83], s[44:45], 0, v[82:83]
	v_lshl_add_u64 v[82:83], s[70:71], 2, v[82:83]
	s_lshl_b32 s16, s86, 2
	v_lshl_add_u64 v[82:83], v[82:83], 0, s[16:17]
	global_store_dword v[82:83], v86, off
.LBB0_1278:
	s_or_b64 exec, exec, s[0:1]
	v_lshl_add_u64 v[92:93], s[42:43], 0, v[32:33]
	v_add_u32_e32 v32, 0x40000, v158
	v_add_u32_e32 v90, 0x40100, v158
	s_waitcnt lgkmcnt(0)
	v_mov_b32_e32 v107, v33
	s_waitcnt vmcnt(17)
	v_lshlrev_b32_e32 v96, 16, v180
	v_and_b32_e32 v97, 0xffff0000, v180
	v_lshl_add_u64 v[94:95], s[42:43], 0, v[106:107]
	v_lshlrev_b32_e32 v102, 16, v181
	v_and_b32_e32 v103, 0xffff0000, v181
	v_lshlrev_b32_e32 v106, 16, v182
	v_and_b32_e32 v107, 0xffff0000, v182
	v_lshlrev_b32_e32 v104, 16, v183
	v_and_b32_e32 v105, 0xffff0000, v183
	v_add_f32_e32 v78, v78, v96
	v_add_f32_e32 v79, v79, v97
	v_add_f32_e32 v80, v80, v102
	v_add_f32_e32 v81, v81, v103
	v_add_f32_e32 v96, v76, v104
	v_add_f32_e32 v97, v77, v105
	v_add_f32_e32 v76, v74, v106
	v_add_f32_e32 v77, v75, v107
	v_cvt_pk_bf16_f32 v74, v78, v79
	v_mul_f32_e32 v79, v79, v79
	v_fmac_f32_e32 v79, v78, v78
	v_mul_f32_e32 v78, v81, v81
	v_fmac_f32_e32 v78, v80, v80
	v_add_f32_e32 v78, v79, v78
	v_mul_f32_e32 v79, v77, v77
	v_fmac_f32_e32 v79, v76, v76
	v_add_f32_e32 v78, v79, v78
	v_mul_f32_e32 v79, v97, v97
	v_fmac_f32_e32 v79, v96, v96
	v_cvt_pk_bf16_f32 v75, v80, v81
	v_add_f32_e32 v91, v79, v78
	v_lshlrev_b32_e32 v78, 16, v186
	v_and_b32_e32 v79, 0xffff0000, v186
	v_lshlrev_b32_e32 v80, 16, v187
	v_and_b32_e32 v81, 0xffff0000, v187
	v_lshlrev_b32_e32 v98, 16, v188
	v_and_b32_e32 v99, 0xffff0000, v188
	v_add_f32_e32 v72, v72, v80
	v_add_f32_e32 v73, v73, v81
	v_add_f32_e32 v70, v70, v78
	v_add_f32_e32 v71, v71, v79
	v_add_f32_e32 v80, v66, v98
	v_add_f32_e32 v81, v67, v99
	v_mul_f32_e32 v66, v71, v71
	v_mul_f32_e32 v67, v73, v73
	v_fmac_f32_e32 v66, v70, v70
	v_fmac_f32_e32 v67, v72, v72
	v_lshlrev_b32_e32 v100, 16, v189
	v_and_b32_e32 v101, 0xffff0000, v189
	v_add_f32_e32 v66, v66, v67
	v_mul_f32_e32 v67, v81, v81
	v_add_f32_e32 v78, v68, v100
	v_add_f32_e32 v79, v69, v101
	v_fmac_f32_e32 v67, v80, v80
	v_add_f32_e32 v66, v67, v66
	v_mul_f32_e32 v67, v79, v79
	v_fmac_f32_e32 v67, v78, v78
	v_add_f32_e32 v66, v67, v66
	v_add_f32_e32 v66, v91, v66
	v_mov_b32_e32 v67, v66
	s_nop 1
	v_permlane16_swap_b32 v67, v66
	v_cvt_pk_bf16_f32 v76, v76, v77
	v_cvt_pk_bf16_f32 v77, v96, v97
	global_store_dwordx4 v[92:93], v[74:77], off
	v_cvt_pk_bf16_f32 v68, v70, v71
	s_waitcnt lgkmcnt(0)
	v_add_f32_e32 v66, v66, v67
	v_mov_b32_e32 v67, v66
	s_nop 1
	v_permlane32_swap_b32 v67, v66
	v_cvt_pk_bf16_f32 v69, v72, v73
	v_cvt_pk_bf16_f32 v70, v80, v81
	v_cvt_pk_bf16_f32 v71, v78, v79
	global_store_dwordx4 v[94:95], v[68:71], off
	s_and_saveexec_b64 s[0:1], vcc
	s_cbranch_execz .LBB0_1280
	v_add_u32_e32 v68, 48, v150
	v_ashrrev_i32_e32 v69, 31, v68
	s_waitcnt lgkmcnt(0)
	v_add_f32_e32 v70, v66, v67
	v_lshlrev_b64 v[66:67], 6, v[68:69]
	v_lshl_add_u64 v[66:67], s[44:45], 0, v[66:67]
	v_lshl_add_u64 v[66:67], s[70:71], 2, v[66:67]
	s_lshl_b32 s16, s86, 2
	v_lshl_add_u64 v[66:67], v[66:67], 0, s[16:17]
	global_store_dword v[66:67], v70, off
.LBB0_1280:
	s_or_b64 exec, exec, s[0:1]
	v_lshl_add_u64 v[76:77], s[42:43], 0, v[32:33]
	v_add_u32_e32 v32, 0x48000, v158
	v_add_u32_e32 v74, 0x48100, v158
	s_waitcnt lgkmcnt(0)
	v_mov_b32_e32 v91, v33
	s_waitcnt vmcnt(18)
	v_lshlrev_b32_e32 v80, 16, v190
	v_and_b32_e32 v81, 0xffff0000, v190
	v_lshl_add_u64 v[78:79], s[42:43], 0, v[90:91]
	v_lshlrev_b32_e32 v86, 16, v191
	v_and_b32_e32 v87, 0xffff0000, v191
	v_lshlrev_b32_e32 v90, 16, v192
	v_and_b32_e32 v91, 0xffff0000, v192
	v_lshlrev_b32_e32 v88, 16, v193
	v_and_b32_e32 v89, 0xffff0000, v193
	v_add_f32_e32 v62, v62, v80
	v_add_f32_e32 v63, v63, v81
	v_add_f32_e32 v64, v64, v86
	v_add_f32_e32 v65, v65, v87
	v_add_f32_e32 v80, v60, v88
	v_add_f32_e32 v81, v61, v89
	v_add_f32_e32 v60, v58, v90
	v_add_f32_e32 v61, v59, v91
	v_cvt_pk_bf16_f32 v58, v62, v63
	v_mul_f32_e32 v63, v63, v63
	v_fmac_f32_e32 v63, v62, v62
	v_mul_f32_e32 v62, v65, v65
	v_fmac_f32_e32 v62, v64, v64
	v_add_f32_e32 v62, v63, v62
	v_mul_f32_e32 v63, v61, v61
	v_fmac_f32_e32 v63, v60, v60
	v_add_f32_e32 v62, v63, v62
	v_mul_f32_e32 v63, v81, v81
	v_fmac_f32_e32 v63, v80, v80
	v_cvt_pk_bf16_f32 v59, v64, v65
	v_add_f32_e32 v75, v63, v62
	v_lshlrev_b32_e32 v62, 16, v202
	v_and_b32_e32 v63, 0xffff0000, v202
	v_lshlrev_b32_e32 v64, 16, v203
	v_and_b32_e32 v65, 0xffff0000, v203
	v_lshlrev_b32_e32 v82, 16, v204
	v_and_b32_e32 v83, 0xffff0000, v204
	v_add_f32_e32 v56, v56, v64
	v_add_f32_e32 v57, v57, v65
	v_add_f32_e32 v54, v54, v62
	v_add_f32_e32 v55, v55, v63
	v_add_f32_e32 v64, v50, v82
	v_add_f32_e32 v65, v51, v83
	v_mul_f32_e32 v50, v55, v55
	v_mul_f32_e32 v51, v57, v57
	v_fmac_f32_e32 v50, v54, v54
	v_fmac_f32_e32 v51, v56, v56
	v_lshlrev_b32_e32 v84, 16, v205
	v_and_b32_e32 v85, 0xffff0000, v205
	v_add_f32_e32 v50, v50, v51
	v_mul_f32_e32 v51, v65, v65
	v_add_f32_e32 v62, v52, v84
	v_add_f32_e32 v63, v53, v85
	v_fmac_f32_e32 v51, v64, v64
	v_add_f32_e32 v50, v51, v50
	v_mul_f32_e32 v51, v63, v63
	v_fmac_f32_e32 v51, v62, v62
	v_add_f32_e32 v50, v51, v50
	v_add_f32_e32 v50, v75, v50
	v_mov_b32_e32 v51, v50
	s_nop 1
	v_permlane16_swap_b32 v51, v50
	v_cvt_pk_bf16_f32 v60, v60, v61
	v_cvt_pk_bf16_f32 v61, v80, v81
	global_store_dwordx4 v[76:77], v[58:61], off
	v_cvt_pk_bf16_f32 v52, v54, v55
	s_waitcnt lgkmcnt(0)
	v_add_f32_e32 v50, v50, v51
	v_mov_b32_e32 v51, v50
	s_nop 1
	v_permlane32_swap_b32 v51, v50
	v_cvt_pk_bf16_f32 v53, v56, v57
	v_cvt_pk_bf16_f32 v54, v64, v65
	v_cvt_pk_bf16_f32 v55, v62, v63
	global_store_dwordx4 v[78:79], v[52:55], off
	s_and_saveexec_b64 s[0:1], vcc
	s_cbranch_execz .LBB0_1282
	v_add_u32_e32 v52, 0x80, v150
	v_ashrrev_i32_e32 v53, 31, v52
	s_waitcnt lgkmcnt(0)
	v_add_f32_e32 v54, v50, v51
	v_lshlrev_b64 v[50:51], 6, v[52:53]
	v_lshl_add_u64 v[50:51], s[44:45], 0, v[50:51]
	v_lshl_add_u64 v[50:51], s[70:71], 2, v[50:51]
	s_lshl_b32 s16, s86, 2
	v_lshl_add_u64 v[50:51], v[50:51], 0, s[16:17]
	global_store_dword v[50:51], v54, off
.LBB0_1282:
	s_or_b64 exec, exec, s[0:1]
	v_lshl_add_u64 v[60:61], s[42:43], 0, v[32:33]
	v_add_u32_e32 v32, 0x50000, v158
	v_add_u32_e32 v58, 0x50100, v158
	s_waitcnt lgkmcnt(0)
	v_mov_b32_e32 v75, v33
	s_waitcnt vmcnt(19)
	v_lshlrev_b32_e32 v64, 16, v206
	v_and_b32_e32 v65, 0xffff0000, v206
	v_lshl_add_u64 v[62:63], s[42:43], 0, v[74:75]
	v_lshlrev_b32_e32 v70, 16, v207
	v_and_b32_e32 v71, 0xffff0000, v207
	v_lshlrev_b32_e32 v74, 16, v208
	v_and_b32_e32 v75, 0xffff0000, v208
	v_lshlrev_b32_e32 v72, 16, v209
	v_and_b32_e32 v73, 0xffff0000, v209
	v_add_f32_e32 v46, v46, v64
	v_add_f32_e32 v47, v47, v65
	v_add_f32_e32 v48, v48, v70
	v_add_f32_e32 v49, v49, v71
	v_add_f32_e32 v64, v44, v72
	v_add_f32_e32 v65, v45, v73
	v_add_f32_e32 v44, v42, v74
	v_add_f32_e32 v45, v43, v75
	v_cvt_pk_bf16_f32 v42, v46, v47
	v_mul_f32_e32 v47, v47, v47
	v_fmac_f32_e32 v47, v46, v46
	v_mul_f32_e32 v46, v49, v49
	v_fmac_f32_e32 v46, v48, v48
	v_add_f32_e32 v46, v47, v46
	v_mul_f32_e32 v47, v45, v45
	v_fmac_f32_e32 v47, v44, v44
	v_add_f32_e32 v46, v47, v46
	v_mul_f32_e32 v47, v65, v65
	v_fmac_f32_e32 v47, v64, v64
	v_cvt_pk_bf16_f32 v43, v48, v49
	v_add_f32_e32 v59, v47, v46
	v_lshlrev_b32_e32 v46, 16, v210
	v_and_b32_e32 v47, 0xffff0000, v210
	v_lshlrev_b32_e32 v48, 16, v211
	v_and_b32_e32 v49, 0xffff0000, v211
	v_lshlrev_b32_e32 v66, 16, v212
	v_and_b32_e32 v67, 0xffff0000, v212
	v_add_f32_e32 v40, v40, v48
	v_add_f32_e32 v41, v41, v49
	v_add_f32_e32 v38, v38, v46
	v_add_f32_e32 v39, v39, v47
	v_add_f32_e32 v48, v34, v66
	v_add_f32_e32 v49, v35, v67
	v_mul_f32_e32 v34, v39, v39
	v_mul_f32_e32 v35, v41, v41
	v_fmac_f32_e32 v34, v38, v38
	v_fmac_f32_e32 v35, v40, v40
	v_lshlrev_b32_e32 v68, 16, v213
	v_and_b32_e32 v69, 0xffff0000, v213
	v_add_f32_e32 v34, v34, v35
	v_mul_f32_e32 v35, v49, v49
	v_add_f32_e32 v46, v36, v68
	v_add_f32_e32 v47, v37, v69
	v_fmac_f32_e32 v35, v48, v48
	v_add_f32_e32 v34, v35, v34
	v_mul_f32_e32 v35, v47, v47
	v_fmac_f32_e32 v35, v46, v46
	v_add_f32_e32 v34, v35, v34
	v_add_f32_e32 v34, v59, v34
	v_mov_b32_e32 v35, v34
	s_nop 1
	v_permlane16_swap_b32 v35, v34
	v_cvt_pk_bf16_f32 v44, v44, v45
	v_cvt_pk_bf16_f32 v45, v64, v65
	global_store_dwordx4 v[60:61], v[42:45], off
	v_cvt_pk_bf16_f32 v36, v38, v39
	s_waitcnt lgkmcnt(0)
	v_add_f32_e32 v34, v34, v35
	v_mov_b32_e32 v35, v34
	s_nop 1
	v_permlane32_swap_b32 v35, v34
	v_cvt_pk_bf16_f32 v37, v40, v41
	v_cvt_pk_bf16_f32 v38, v48, v49
	v_cvt_pk_bf16_f32 v39, v46, v47
	global_store_dwordx4 v[62:63], v[36:39], off
	s_and_saveexec_b64 s[0:1], vcc
	s_cbranch_execz .LBB0_1284
	v_add_u32_e32 v36, 0x90, v150
	v_ashrrev_i32_e32 v37, 31, v36
	s_waitcnt lgkmcnt(0)
	v_add_f32_e32 v38, v34, v35
	v_lshlrev_b64 v[34:35], 6, v[36:37]
	v_lshl_add_u64 v[34:35], s[44:45], 0, v[34:35]
	v_lshl_add_u64 v[34:35], s[70:71], 2, v[34:35]
	s_lshl_b32 s16, s86, 2
	v_lshl_add_u64 v[34:35], v[34:35], 0, s[16:17]
	global_store_dword v[34:35], v38, off
.LBB0_1284:
	s_or_b64 exec, exec, s[0:1]
	v_lshl_add_u64 v[44:45], s[42:43], 0, v[32:33]
	v_add_u32_e32 v32, 0x58000, v158
	v_add_u32_e32 v42, 0x58100, v158
	s_waitcnt lgkmcnt(0)
	v_mov_b32_e32 v59, v33
	s_waitcnt vmcnt(20)
	v_lshlrev_b32_e32 v48, 16, v214
	v_and_b32_e32 v49, 0xffff0000, v214
	v_lshl_add_u64 v[46:47], s[42:43], 0, v[58:59]
	v_lshlrev_b32_e32 v54, 16, v215
	v_and_b32_e32 v55, 0xffff0000, v215
	v_lshlrev_b32_e32 v58, 16, v216
	v_and_b32_e32 v59, 0xffff0000, v216
	v_lshlrev_b32_e32 v56, 16, v217
	v_and_b32_e32 v57, 0xffff0000, v217
	v_add_f32_e32 v28, v28, v48
	v_add_f32_e32 v29, v29, v49
	v_add_f32_e32 v30, v30, v54
	v_add_f32_e32 v31, v31, v55
	v_add_f32_e32 v48, v26, v56
	v_add_f32_e32 v49, v27, v57
	v_add_f32_e32 v26, v24, v58
	v_add_f32_e32 v27, v25, v59
	v_cvt_pk_bf16_f32 v24, v28, v29
	v_mul_f32_e32 v29, v29, v29
	v_fmac_f32_e32 v29, v28, v28
	v_mul_f32_e32 v28, v31, v31
	v_fmac_f32_e32 v28, v30, v30
	v_add_f32_e32 v28, v29, v28
	v_mul_f32_e32 v29, v27, v27
	v_fmac_f32_e32 v29, v26, v26
	v_add_f32_e32 v28, v29, v28
	v_mul_f32_e32 v29, v49, v49
	v_fmac_f32_e32 v29, v48, v48
	v_cvt_pk_bf16_f32 v25, v30, v31
	v_add_f32_e32 v43, v29, v28
	v_lshlrev_b32_e32 v28, 16, v218
	v_and_b32_e32 v29, 0xffff0000, v218
	v_lshlrev_b32_e32 v30, 16, v219
	v_and_b32_e32 v31, 0xffff0000, v219
	v_lshlrev_b32_e32 v50, 16, v220
	v_and_b32_e32 v51, 0xffff0000, v220
	v_add_f32_e32 v22, v22, v30
	v_add_f32_e32 v23, v23, v31
	v_add_f32_e32 v20, v20, v28
	v_add_f32_e32 v21, v21, v29
	v_add_f32_e32 v30, v16, v50
	v_add_f32_e32 v31, v17, v51
	v_mul_f32_e32 v16, v21, v21
	v_mul_f32_e32 v17, v23, v23
	v_fmac_f32_e32 v16, v20, v20
	v_fmac_f32_e32 v17, v22, v22
	v_lshlrev_b32_e32 v52, 16, v221
	v_and_b32_e32 v53, 0xffff0000, v221
	v_add_f32_e32 v16, v16, v17
	v_mul_f32_e32 v17, v31, v31
	v_add_f32_e32 v28, v18, v52
	v_add_f32_e32 v29, v19, v53
	v_fmac_f32_e32 v17, v30, v30
	v_add_f32_e32 v16, v17, v16
	v_mul_f32_e32 v17, v29, v29
	v_fmac_f32_e32 v17, v28, v28
	v_add_f32_e32 v16, v17, v16
	v_add_f32_e32 v16, v43, v16
	v_mov_b32_e32 v17, v16
	s_nop 1
	v_permlane16_swap_b32 v17, v16
	v_cvt_pk_bf16_f32 v26, v26, v27
	v_cvt_pk_bf16_f32 v27, v48, v49
	global_store_dwordx4 v[44:45], v[24:27], off
	v_cvt_pk_bf16_f32 v18, v20, v21
	s_waitcnt lgkmcnt(0)
	v_add_f32_e32 v16, v16, v17
	v_mov_b32_e32 v17, v16
	s_nop 1
	v_permlane32_swap_b32 v17, v16
	v_cvt_pk_bf16_f32 v19, v22, v23
	v_cvt_pk_bf16_f32 v20, v30, v31
	v_cvt_pk_bf16_f32 v21, v28, v29
	global_store_dwordx4 v[46:47], v[18:21], off
	s_and_saveexec_b64 s[0:1], vcc
	s_cbranch_execz .LBB0_1286
	v_add_u32_e32 v18, 0xa0, v150
	v_ashrrev_i32_e32 v19, 31, v18
	s_waitcnt lgkmcnt(0)
	v_add_f32_e32 v20, v16, v17
	v_lshlrev_b64 v[16:17], 6, v[18:19]
	v_lshl_add_u64 v[16:17], s[44:45], 0, v[16:17]
	v_lshl_add_u64 v[16:17], s[70:71], 2, v[16:17]
	s_lshl_b32 s16, s86, 2
	v_lshl_add_u64 v[16:17], v[16:17], 0, s[16:17]
	global_store_dword v[16:17], v20, off
.LBB0_1286:
	s_or_b64 exec, exec, s[0:1]
	s_waitcnt vmcnt(15)
	v_lshlrev_b32_e32 v20, 16, v134
	v_and_b32_e32 v21, 0xffff0000, v134
	v_lshlrev_b32_e32 v22, 16, v135
	v_and_b32_e32 v23, 0xffff0000, v135
	v_lshlrev_b32_e32 v24, 16, v136
	v_and_b32_e32 v25, 0xffff0000, v136
	v_lshlrev_b32_e32 v26, 16, v137
	v_and_b32_e32 v27, 0xffff0000, v137
	v_add_f32_e32 v12, v12, v20
	v_add_f32_e32 v13, v13, v21
	v_add_f32_e32 v14, v14, v22
	v_add_f32_e32 v15, v15, v23
	v_add_f32_e32 v20, v10, v26
	v_add_f32_e32 v21, v11, v27
	v_add_f32_e32 v10, v8, v24
	v_add_f32_e32 v11, v9, v25
	v_cvt_pk_bf16_f32 v8, v12, v13
	v_mul_f32_e32 v13, v13, v13
	v_fmac_f32_e32 v13, v12, v12
	v_mul_f32_e32 v12, v15, v15
	v_fmac_f32_e32 v12, v14, v14
	v_add_f32_e32 v12, v13, v12
	v_mul_f32_e32 v13, v11, v11
	v_fmac_f32_e32 v13, v10, v10
	v_add_f32_e32 v12, v13, v12
	v_mul_f32_e32 v13, v21, v21
	v_fmac_f32_e32 v13, v20, v20
	v_cvt_pk_bf16_f32 v9, v14, v15
	v_add_f32_e32 v26, v13, v12
	v_lshlrev_b32_e32 v12, 16, v130
	v_and_b32_e32 v13, 0xffff0000, v130
	v_lshlrev_b32_e32 v14, 16, v131
	v_and_b32_e32 v15, 0xffff0000, v131
	v_lshlrev_b32_e32 v22, 16, v132
	v_and_b32_e32 v23, 0xffff0000, v132
	v_add_f32_e32 v6, v6, v14
	v_add_f32_e32 v7, v7, v15
	v_add_f32_e32 v4, v4, v12
	v_add_f32_e32 v5, v5, v13
	v_add_f32_e32 v14, v0, v22
	v_add_f32_e32 v15, v1, v23
	v_mul_f32_e32 v0, v5, v5
	v_mul_f32_e32 v1, v7, v7
	v_fmac_f32_e32 v0, v4, v4
	v_fmac_f32_e32 v1, v6, v6
	v_lshlrev_b32_e32 v24, 16, v133
	v_and_b32_e32 v25, 0xffff0000, v133
	v_add_f32_e32 v0, v0, v1
	v_mul_f32_e32 v1, v15, v15
	v_add_f32_e32 v12, v2, v24
	v_add_f32_e32 v13, v3, v25
	v_fmac_f32_e32 v1, v14, v14
	v_add_f32_e32 v0, v1, v0
	v_mul_f32_e32 v1, v13, v13
	v_fmac_f32_e32 v1, v12, v12
	v_add_f32_e32 v0, v1, v0
	v_add_f32_e32 v0, v26, v0
	v_mov_b32_e32 v1, v0
	s_nop 1
	v_permlane16_swap_b32 v1, v0
	v_mov_b32_e32 v43, v33
	s_waitcnt lgkmcnt(1)
	v_lshl_add_u64 v[16:17], s[42:43], 0, v[32:33]
	v_lshl_add_u64 v[18:19], s[42:43], 0, v[42:43]
	v_cvt_pk_bf16_f32 v10, v10, v11
	s_waitcnt lgkmcnt(0)
	v_add_f32_e32 v0, v0, v1
	v_mov_b32_e32 v1, v0
	s_nop 1
	v_permlane32_swap_b32 v1, v0
	v_cvt_pk_bf16_f32 v11, v20, v21
	global_store_dwordx4 v[16:17], v[8:11], off
	v_cvt_pk_bf16_f32 v2, v4, v5
	v_cvt_pk_bf16_f32 v3, v6, v7
	v_cvt_pk_bf16_f32 v4, v14, v15
	v_cvt_pk_bf16_f32 v5, v12, v13
	global_store_dwordx4 v[18:19], v[2:5], off
	s_and_saveexec_b64 s[0:1], vcc
	s_cbranch_execz .LBB0_1288
	v_add_u32_e32 v2, 0xb0, v150
	v_ashrrev_i32_e32 v3, 31, v2
	s_waitcnt lgkmcnt(0)
	v_add_f32_e32 v4, v0, v1
	v_lshlrev_b64 v[0:1], 6, v[2:3]
	v_lshl_add_u64 v[0:1], s[44:45], 0, v[0:1]
	v_lshl_add_u64 v[0:1], s[70:71], 2, v[0:1]
	s_lshl_b32 s16, s86, 2
	v_lshl_add_u64 v[0:1], v[0:1], 0, s[16:17]
	global_store_dword v[0:1], v4, off
